# K loop: s_nop pads between m0 write and LDS-DMA replaced by the second DMA address add (m0 write moved ahead of it)
# baseline (speedup 1.0000x reference)
.LBB0_522:
	s_add_i32 vcc_lo, s74, 2
	s_add_u32 s76, s72, 0x80
	s_addc_u32 s75, s73, 0
	s_add_i32 vcc_hi, 0, 0x10000
	v_add_u32_e32 v140, vcc_hi, v237
	s_waitcnt lgkmcnt(0)
	ds_read_b128 v[128:131], v140
	ds_read_b128 v[132:135], v140 offset:1024
	ds_read_b128 v[136:139], v140 offset:2048
	ds_read_b128 v[140:143], v140 offset:3072
	s_cmp_eq_u32 s50, s74
	s_cselect_b32 s74, s68, s76
	s_cselect_b32 s75, s69, s75
	s_cselect_b32 s77, s71, s79
	s_cselect_b32 s76, s70, s78
	v_lshl_add_u64 v[176:177], s[72:73], 0, v[206:207]
	s_add_i32 m0, s93, 0xc000
	ds_read_b128 v[144:147], v240
	ds_read_b128 v[148:151], v240 offset:1024
	ds_read_b128 v[152:155], v240 offset:2048
	ds_read_b128 v[156:159], v240 offset:3072
	ds_read_b128 v[160:163], v240 offset:4096
	ds_read_b128 v[164:167], v240 offset:5120
	ds_read_b128 v[168:171], v240 offset:6144
	ds_read_b128 v[172:175], v240 offset:7168
	global_load_lds_dwordx4 v[176:177], off
	s_add_i32 m0, s93, 0xe000
	v_lshl_add_u64 v[176:177], s[72:73], 0, v[208:209]
	global_load_lds_dwordx4 v[176:177], off
	s_waitcnt lgkmcnt(8)
	s_barrier
	s_waitcnt lgkmcnt(0)
	v_mfma_f32_16x16x32_bf16 v[124:127], v[128:131], v[144:147], v[124:127]
	v_mfma_f32_16x16x32_bf16 v[120:123], v[136:139], v[144:147], v[120:123]
	v_mfma_f32_16x16x32_bf16 v[116:119], v[128:131], v[152:155], v[116:119]
	v_mfma_f32_16x16x32_bf16 v[112:115], v[136:139], v[152:155], v[112:115]
	v_mfma_f32_16x16x32_bf16 v[100:103], v[128:131], v[160:163], v[100:103]
	v_mfma_f32_16x16x32_bf16 v[96:99], v[136:139], v[160:163], v[96:99]
	v_mfma_f32_16x16x32_bf16 v[84:87], v[128:131], v[168:171], v[84:87]
	v_mfma_f32_16x16x32_bf16 v[80:83], v[136:139], v[168:171], v[80:83]
	v_mfma_f32_16x16x32_bf16 v[124:127], v[132:135], v[148:151], v[124:127]
	s_add_i32 s31, 0, 0x14000
	v_mfma_f32_16x16x32_bf16 v[120:123], v[140:143], v[148:151], v[120:123]
	s_add_i32 vcc_hi, vcc_hi, s87
	v_mfma_f32_16x16x32_bf16 v[116:119], v[132:135], v[156:159], v[116:119]
	v_add_u32_e32 v188, s31, v237
	v_mfma_f32_16x16x32_bf16 v[112:115], v[140:143], v[156:159], v[112:115]
	v_lshl_add_u64 v[210:211], s[76:77], 0, v[196:197]
	v_mfma_f32_16x16x32_bf16 v[100:103], v[132:135], v[164:167], v[100:103]
	s_mov_b32 m0, vcc_hi
	v_mfma_f32_16x16x32_bf16 v[96:99], v[140:143], v[164:167], v[96:99]
	v_mfma_f32_16x16x32_bf16 v[84:87], v[132:135], v[172:175], v[84:87]
	v_mfma_f32_16x16x32_bf16 v[80:83], v[140:143], v[172:175], v[80:83]
	s_barrier
	ds_read_b128 v[176:179], v188
	ds_read_b128 v[180:183], v188 offset:1024
	ds_read_b128 v[184:187], v188 offset:2048
	ds_read_b128 v[188:191], v188 offset:3072
	global_load_lds_dwordx4 v[210:211], off
	s_add_i32 m0, vcc_hi, 0x2000
	v_lshl_add_u64 v[212:213], s[76:77], 0, v[200:201]
	global_load_lds_dwordx4 v[212:213], off
	s_barrier
	s_waitcnt lgkmcnt(0)
	v_mfma_f32_16x16x32_bf16 v[108:111], v[176:179], v[144:147], v[108:111]
	v_mfma_f32_16x16x32_bf16 v[104:107], v[184:187], v[144:147], v[104:107]
	v_mfma_f32_16x16x32_bf16 v[92:95], v[176:179], v[152:155], v[92:95]
	v_mfma_f32_16x16x32_bf16 v[88:91], v[184:187], v[152:155], v[88:91]
	v_mfma_f32_16x16x32_bf16 v[76:79], v[176:179], v[160:163], v[76:79]
	v_mfma_f32_16x16x32_bf16 v[72:75], v[184:187], v[160:163], v[72:75]
	v_mfma_f32_16x16x32_bf16 v[68:71], v[176:179], v[168:171], v[68:71]
	v_mfma_f32_16x16x32_bf16 v[64:67], v[184:187], v[168:171], v[64:67]
	v_mfma_f32_16x16x32_bf16 v[108:111], v[180:183], v[148:151], v[108:111]
	s_mov_b32 m0, s93
	v_mfma_f32_16x16x32_bf16 v[104:107], v[188:191], v[148:151], v[104:107]
	v_lshl_add_u64 v[214:215], s[74:75], 0, v[194:195]
	v_mfma_f32_16x16x32_bf16 v[92:95], v[180:183], v[156:159], v[92:95]
	v_mfma_f32_16x16x32_bf16 v[88:91], v[188:191], v[156:159], v[88:91]
	v_mfma_f32_16x16x32_bf16 v[76:79], v[180:183], v[164:167], v[76:79]
	v_mfma_f32_16x16x32_bf16 v[72:75], v[188:191], v[164:167], v[72:75]
	v_mfma_f32_16x16x32_bf16 v[68:71], v[180:183], v[172:175], v[68:71]
	v_mfma_f32_16x16x32_bf16 v[64:67], v[188:191], v[172:175], v[64:67]
	s_barrier
	ds_read_b128 v[144:147], v240 offset:16384
	ds_read_b128 v[148:151], v240 offset:17408
	ds_read_b128 v[152:155], v240 offset:18432
	ds_read_b128 v[156:159], v240 offset:19456
	ds_read_b128 v[160:163], v240 offset:20480
	ds_read_b128 v[164:167], v240 offset:21504
	ds_read_b128 v[168:171], v240 offset:22528
	ds_read_b128 v[172:175], v240 offset:23552
	global_load_lds_dwordx4 v[214:215], off
	s_mov_b32 m0, s54
	v_lshl_add_u64 v[216:217], s[74:75], 0, v[198:199]
	global_load_lds_dwordx4 v[216:217], off
	s_barrier
	s_waitcnt lgkmcnt(0)
	v_mfma_f32_16x16x32_bf16 v[60:63], v[128:131], v[144:147], v[60:63]
	v_mfma_f32_16x16x32_bf16 v[56:59], v[136:139], v[144:147], v[56:59]
	v_mfma_f32_16x16x32_bf16 v[52:55], v[128:131], v[152:155], v[52:55]
	v_mfma_f32_16x16x32_bf16 v[48:51], v[136:139], v[152:155], v[48:51]
	v_mfma_f32_16x16x32_bf16 v[36:39], v[128:131], v[160:163], v[36:39]
	v_mfma_f32_16x16x32_bf16 v[32:35], v[136:139], v[160:163], v[32:35]
	v_mfma_f32_16x16x32_bf16 v[20:23], v[128:131], v[168:171], v[20:23]
	v_mfma_f32_16x16x32_bf16 v[16:19], v[136:139], v[168:171], v[16:19]
	v_mfma_f32_16x16x32_bf16 v[60:63], v[132:135], v[148:151], v[60:63]
	s_add_u32 s76, s76, s20
	v_mfma_f32_16x16x32_bf16 v[56:59], v[140:143], v[148:151], v[56:59]
	s_addc_u32 s77, s77, 0
	v_mfma_f32_16x16x32_bf16 v[52:55], v[132:135], v[156:159], v[52:55]
	s_add_i32 s31, s31, s87
	v_mfma_f32_16x16x32_bf16 v[48:51], v[140:143], v[156:159], v[48:51]
	v_lshl_add_u64 v[218:219], s[76:77], 0, v[196:197]
	v_mfma_f32_16x16x32_bf16 v[36:39], v[132:135], v[164:167], v[36:39]
	s_mov_b32 m0, s31
	v_mfma_f32_16x16x32_bf16 v[32:35], v[140:143], v[164:167], v[32:35]
	v_lshl_add_u64 v[220:221], s[76:77], 0, v[200:201]
	v_mfma_f32_16x16x32_bf16 v[20:23], v[132:135], v[172:175], v[20:23]
	v_mfma_f32_16x16x32_bf16 v[16:19], v[140:143], v[172:175], v[16:19]
	s_barrier
	global_load_lds_dwordx4 v[218:219], off
	s_add_i32 m0, s31, 0x2000
	s_nop 0
	global_load_lds_dwordx4 v[220:221], off
	s_waitcnt vmcnt(6)
	s_barrier
	v_mfma_f32_16x16x32_bf16 v[44:47], v[176:179], v[144:147], v[44:47]
	v_mfma_f32_16x16x32_bf16 v[40:43], v[184:187], v[144:147], v[40:43]
	v_mfma_f32_16x16x32_bf16 v[28:31], v[176:179], v[152:155], v[28:31]
	v_mfma_f32_16x16x32_bf16 v[24:27], v[184:187], v[152:155], v[24:27]
	v_mfma_f32_16x16x32_bf16 v[12:15], v[176:179], v[160:163], v[12:15]
	v_mfma_f32_16x16x32_bf16 v[8:11], v[184:187], v[160:163], v[8:11]
	v_mfma_f32_16x16x32_bf16 v[4:7], v[176:179], v[168:171], v[4:7]
	v_mfma_f32_16x16x32_bf16 v[0:3], v[184:187], v[168:171], v[0:3]
	v_mfma_f32_16x16x32_bf16 v[44:47], v[180:183], v[148:151], v[44:47]
	s_add_i32 s31, 0, 0x18000
	v_mfma_f32_16x16x32_bf16 v[40:43], v[188:191], v[148:151], v[40:43]
	v_add_u32_e32 v140, s31, v237
	v_mfma_f32_16x16x32_bf16 v[28:31], v[180:183], v[156:159], v[28:31]
	v_mfma_f32_16x16x32_bf16 v[24:27], v[188:191], v[156:159], v[24:27]
	v_mfma_f32_16x16x32_bf16 v[12:15], v[180:183], v[164:167], v[12:15]
	v_mfma_f32_16x16x32_bf16 v[8:11], v[188:191], v[164:167], v[8:11]
	v_mfma_f32_16x16x32_bf16 v[4:7], v[180:183], v[172:175], v[4:7]
	v_mfma_f32_16x16x32_bf16 v[0:3], v[188:191], v[172:175], v[0:3]
	s_barrier
	ds_read_b128 v[128:131], v140
	ds_read_b128 v[132:135], v140 offset:1024
	ds_read_b128 v[136:139], v140 offset:2048
	ds_read_b128 v[140:143], v140 offset:3072
	s_add_u32 s74, s74, s20
	s_addc_u32 s75, s75, 0
	s_mov_b32 m0, s34
	v_lshl_add_u64 v[176:177], s[74:75], 0, v[194:195]
	ds_read_b128 v[144:147], v240 offset:32768
	ds_read_b128 v[148:151], v240 offset:33792
	ds_read_b128 v[152:155], v240 offset:34816
	ds_read_b128 v[156:159], v240 offset:35840
	ds_read_b128 v[160:163], v240 offset:36864
	ds_read_b128 v[164:167], v240 offset:37888
	ds_read_b128 v[168:171], v240 offset:38912
	ds_read_b128 v[172:175], v240 offset:39936
	global_load_lds_dwordx4 v[176:177], off
	s_mov_b32 m0, s35
	v_lshl_add_u64 v[176:177], s[74:75], 0, v[198:199]
	global_load_lds_dwordx4 v[176:177], off
	s_waitcnt lgkmcnt(8)
	s_barrier
	s_waitcnt lgkmcnt(0)
	v_mfma_f32_16x16x32_bf16 v[124:127], v[128:131], v[144:147], v[124:127]
	v_mfma_f32_16x16x32_bf16 v[120:123], v[136:139], v[144:147], v[120:123]
	v_mfma_f32_16x16x32_bf16 v[116:119], v[128:131], v[152:155], v[116:119]
	v_mfma_f32_16x16x32_bf16 v[112:115], v[136:139], v[152:155], v[112:115]
	v_mfma_f32_16x16x32_bf16 v[100:103], v[128:131], v[160:163], v[100:103]
	v_mfma_f32_16x16x32_bf16 v[96:99], v[136:139], v[160:163], v[96:99]
	v_mfma_f32_16x16x32_bf16 v[84:87], v[128:131], v[168:171], v[84:87]
	v_mfma_f32_16x16x32_bf16 v[80:83], v[136:139], v[168:171], v[80:83]
	v_mfma_f32_16x16x32_bf16 v[124:127], v[132:135], v[148:151], v[124:127]
	s_add_i32 s74, 0, 0x1c000
	v_mfma_f32_16x16x32_bf16 v[120:123], v[140:143], v[148:151], v[120:123]
	s_add_i32 s31, s31, s87
	v_mfma_f32_16x16x32_bf16 v[116:119], v[132:135], v[156:159], v[116:119]
	v_add_u32_e32 v188, s74, v237
	v_mfma_f32_16x16x32_bf16 v[112:115], v[140:143], v[156:159], v[112:115]
	v_lshl_add_u64 v[210:211], v[210:211], 0, s[60:61]
	v_mfma_f32_16x16x32_bf16 v[100:103], v[132:135], v[164:167], v[100:103]
	s_mov_b32 m0, s31
	v_mfma_f32_16x16x32_bf16 v[96:99], v[140:143], v[164:167], v[96:99]
	v_mfma_f32_16x16x32_bf16 v[84:87], v[132:135], v[172:175], v[84:87]
	v_mfma_f32_16x16x32_bf16 v[80:83], v[140:143], v[172:175], v[80:83]
	s_barrier
	ds_read_b128 v[176:179], v188
	ds_read_b128 v[180:183], v188 offset:1024
	ds_read_b128 v[184:187], v188 offset:2048
	ds_read_b128 v[188:191], v188 offset:3072
	global_load_lds_dwordx4 v[210:211], off
	s_add_i32 m0, s31, 0x2000
	v_lshl_add_u64 v[210:211], v[212:213], 0, s[60:61]
	global_load_lds_dwordx4 v[210:211], off
	s_barrier
	s_waitcnt lgkmcnt(0)
	v_mfma_f32_16x16x32_bf16 v[108:111], v[176:179], v[144:147], v[108:111]
	v_mfma_f32_16x16x32_bf16 v[104:107], v[184:187], v[144:147], v[104:107]
	v_mfma_f32_16x16x32_bf16 v[92:95], v[176:179], v[152:155], v[92:95]
	v_mfma_f32_16x16x32_bf16 v[88:91], v[184:187], v[152:155], v[88:91]
	v_mfma_f32_16x16x32_bf16 v[76:79], v[176:179], v[160:163], v[76:79]
	v_mfma_f32_16x16x32_bf16 v[72:75], v[184:187], v[160:163], v[72:75]
	v_mfma_f32_16x16x32_bf16 v[68:71], v[176:179], v[168:171], v[68:71]
	v_mfma_f32_16x16x32_bf16 v[64:67], v[184:187], v[168:171], v[64:67]
	v_mfma_f32_16x16x32_bf16 v[108:111], v[180:183], v[148:151], v[108:111]
	s_mov_b32 m0, s97
	v_mfma_f32_16x16x32_bf16 v[104:107], v[188:191], v[148:151], v[104:107]
	v_lshl_add_u64 v[210:211], v[214:215], 0, s[60:61]
	v_mfma_f32_16x16x32_bf16 v[92:95], v[180:183], v[156:159], v[92:95]
	v_mfma_f32_16x16x32_bf16 v[88:91], v[188:191], v[156:159], v[88:91]
	v_mfma_f32_16x16x32_bf16 v[76:79], v[180:183], v[164:167], v[76:79]
	v_mfma_f32_16x16x32_bf16 v[72:75], v[188:191], v[164:167], v[72:75]
	v_mfma_f32_16x16x32_bf16 v[68:71], v[180:183], v[172:175], v[68:71]
	v_mfma_f32_16x16x32_bf16 v[64:67], v[188:191], v[172:175], v[64:67]
	s_barrier
	ds_read_b128 v[144:147], v240 offset:49152
	ds_read_b128 v[148:151], v240 offset:50176
	ds_read_b128 v[152:155], v240 offset:51200
	ds_read_b128 v[156:159], v240 offset:52224
	ds_read_b128 v[160:163], v240 offset:53248
	ds_read_b128 v[164:167], v240 offset:54272
	ds_read_b128 v[168:171], v240 offset:55296
	ds_read_b128 v[172:175], v240 offset:56320
	global_load_lds_dwordx4 v[210:211], off
	s_mov_b32 m0, s36
	v_lshl_add_u64 v[210:211], v[216:217], 0, s[60:61]
	global_load_lds_dwordx4 v[210:211], off
	s_barrier
	s_waitcnt lgkmcnt(0)
	v_mfma_f32_16x16x32_bf16 v[60:63], v[128:131], v[144:147], v[60:63]
	v_mfma_f32_16x16x32_bf16 v[56:59], v[136:139], v[144:147], v[56:59]
	v_mfma_f32_16x16x32_bf16 v[52:55], v[128:131], v[152:155], v[52:55]
	v_mfma_f32_16x16x32_bf16 v[48:51], v[136:139], v[152:155], v[48:51]
	v_mfma_f32_16x16x32_bf16 v[36:39], v[128:131], v[160:163], v[36:39]
	v_mfma_f32_16x16x32_bf16 v[32:35], v[136:139], v[160:163], v[32:35]
	v_mfma_f32_16x16x32_bf16 v[20:23], v[128:131], v[168:171], v[20:23]
	v_mfma_f32_16x16x32_bf16 v[16:19], v[136:139], v[168:171], v[16:19]
	v_mfma_f32_16x16x32_bf16 v[60:63], v[132:135], v[148:151], v[60:63]
	s_add_i32 s31, s74, s87
	v_mfma_f32_16x16x32_bf16 v[56:59], v[140:143], v[148:151], v[56:59]
	v_lshl_add_u64 v[128:129], v[218:219], 0, s[60:61]
	v_mfma_f32_16x16x32_bf16 v[52:55], v[132:135], v[156:159], v[52:55]
	s_mov_b32 m0, s31
	v_mfma_f32_16x16x32_bf16 v[48:51], v[140:143], v[156:159], v[48:51]
	v_mfma_f32_16x16x32_bf16 v[36:39], v[132:135], v[164:167], v[36:39]
	v_mfma_f32_16x16x32_bf16 v[32:35], v[140:143], v[164:167], v[32:35]
	v_mfma_f32_16x16x32_bf16 v[20:23], v[132:135], v[172:175], v[20:23]
	v_mfma_f32_16x16x32_bf16 v[16:19], v[140:143], v[172:175], v[16:19]
	s_barrier
	s_nop 0
	global_load_lds_dwordx4 v[128:129], off
	s_add_i32 m0, s31, 0x2000
	v_lshl_add_u64 v[128:129], v[220:221], 0, s[60:61]
	global_load_lds_dwordx4 v[128:129], off
	s_waitcnt vmcnt(6)
	s_barrier
	v_mfma_f32_16x16x32_bf16 v[44:47], v[176:179], v[144:147], v[44:47]
	v_mfma_f32_16x16x32_bf16 v[40:43], v[184:187], v[144:147], v[40:43]
	v_mfma_f32_16x16x32_bf16 v[28:31], v[176:179], v[152:155], v[28:31]
	v_mfma_f32_16x16x32_bf16 v[24:27], v[184:187], v[152:155], v[24:27]
	v_mfma_f32_16x16x32_bf16 v[12:15], v[176:179], v[160:163], v[12:15]
	v_mfma_f32_16x16x32_bf16 v[8:11], v[184:187], v[160:163], v[8:11]
	v_mfma_f32_16x16x32_bf16 v[4:7], v[176:179], v[168:171], v[4:7]
	v_mfma_f32_16x16x32_bf16 v[0:3], v[184:187], v[168:171], v[0:3]
	v_mfma_f32_16x16x32_bf16 v[44:47], v[180:183], v[148:151], v[44:47]
	s_add_u32 s72, s72, 0x100
	v_mfma_f32_16x16x32_bf16 v[40:43], v[188:191], v[148:151], v[40:43]
	s_addc_u32 s73, s73, 0
	v_mfma_f32_16x16x32_bf16 v[28:31], v[180:183], v[156:159], v[28:31]
	s_add_u32 s78, s78, 0x100
	v_mfma_f32_16x16x32_bf16 v[24:27], v[188:191], v[156:159], v[24:27]
	s_addc_u32 s79, s79, 0
	v_mfma_f32_16x16x32_bf16 v[12:15], v[180:183], v[164:167], v[12:15]
	s_cmp_ge_u32 vcc_lo, s30
	v_mfma_f32_16x16x32_bf16 v[8:11], v[188:191], v[164:167], v[8:11]
	s_mov_b32 s74, vcc_lo
	v_mfma_f32_16x16x32_bf16 v[4:7], v[180:183], v[172:175], v[4:7]
	v_mfma_f32_16x16x32_bf16 v[0:3], v[188:191], v[172:175], v[0:3]
	s_barrier
	s_cbranch_scc0 .LBB0_522
	s_cmp_lt_i32 s91, 0
	s_mov_b64 s[72:73], -1
	s_cbranch_scc0 .LBB0_716
	s_lshl_b32 s78, s46, 8
	s_cmp_lt_i32 s81, 2
	s_cbranch_scc1 .LBB0_582
	s_cmp_lt_i32 s81, 3
	s_cbranch_scc1 .LBB0_579
	s_cmp_lg_u32 s81, 3
	s_cbranch_scc0 .LBB0_544
	v_lshl_or_b32 v128, s19, 7, v238
	v_ashrrev_i32_e32 v129, 31, v128
	v_lshl_add_u64 v[144:145], v[128:129], 1, s[24:25]
	v_and_b32_e32 v129, 64, v231
	v_xor_b32_e32 v128, 16, v231
	v_add_u32_e32 v129, 64, v129
	v_cmp_lt_i32_e32 vcc, v128, v129
	v_add_u32_e32 v146, s78, v202
	v_ashrrev_i32_e32 v147, 31, v146
	v_cndmask_b32_e32 v128, v231, v128, vcc
	v_lshlrev_b32_e32 v167, 2, v128
	v_xor_b32_e32 v128, 32, v231
	v_cmp_lt_i32_e32 vcc, v128, v129
	v_or_b32_e32 v156, 16, v146
	v_ashrrev_i32_e32 v157, 31, v156
	v_cndmask_b32_e32 v128, v231, v128, vcc
	v_lshlrev_b32_e32 v166, 2, v128
	v_lshlrev_b64 v[128:129], 12, v[146:147]
	v_lshl_add_u64 v[160:161], v[144:145], 0, v[128:129]
	global_load_dwordx4 v[140:143], v[160:161], off
	v_or_b32_e32 v152, 32, v146
	v_lshlrev_b64 v[128:129], 12, v[156:157]
	v_ashrrev_i32_e32 v153, 31, v152
	v_or_b32_e32 v148, 48, v146
	v_lshl_add_u64 v[158:159], v[144:145], 0, v[128:129]
	v_lshlrev_b64 v[128:129], 12, v[152:153]
	v_ashrrev_i32_e32 v149, 31, v148
	v_lshl_add_u64 v[154:155], v[144:145], 0, v[128:129]
	v_lshlrev_b64 v[128:129], 12, v[148:149]
	v_lshl_add_u64 v[150:151], v[144:145], 0, v[128:129]
	global_load_dwordx4 v[136:139], v[158:159], off
	global_load_dwordx4 v[132:135], v[154:155], off
	global_load_dwordx4 v[128:131], v[150:151], off
	v_mul_f32_e32 v163, 0xbfb8aa3b, v104
	v_exp_f32_e32 v163, v163
	v_mul_f32_e32 v162, 0xbfb8aa3b, v108
	v_exp_f32_e32 v162, v162
	v_add_f32_e32 v163, 1.0, v163
	v_rcp_f32_e32 v164, v163
	v_mul_f32_e32 v163, 0xbfb8aa3b, v109
	v_exp_f32_e32 v163, v163
	v_add_f32_e32 v162, 1.0, v162
	v_rcp_f32_e32 v162, v162
	v_add_f32_e32 v163, 1.0, v163
	v_rcp_f32_e32 v163, v163
	s_waitcnt vmcnt(0)
	v_lshlrev_b32_e32 v168, 16, v140
	v_and_b32_e32 v169, 0xffff0000, v140
	v_mul_f32_e32 v140, 0xbfb8aa3b, v105
	v_exp_f32_e32 v140, v140
	v_pk_fma_f32 v[162:163], v[162:163], v[124:125], v[168:169]
	v_lshlrev_b32_e32 v168, 16, v142
	v_and_b32_e32 v169, 0xffff0000, v142
	v_add_f32_e32 v140, 1.0, v140
	v_rcp_f32_e32 v165, v140
	v_mul_f32_e32 v140, 0xbfb8aa3b, v110
	v_exp_f32_e32 v140, v140
	v_mul_f32_e32 v142, 0xbfb8aa3b, v111
	v_pk_fma_f32 v[164:165], v[164:165], v[120:121], v[168:169]
	v_lshlrev_b32_e32 v170, 16, v141
	v_add_f32_e32 v140, 1.0, v140
	v_rcp_f32_e32 v168, v140
	v_mul_f32_e32 v140, 0xbfb8aa3b, v106
	v_and_b32_e32 v171, 0xffff0000, v141
	v_mul_f32_e32 v141, 0xbfb8aa3b, v107
	v_exp_f32_e32 v140, v140
	v_exp_f32_e32 v142, v142
	v_exp_f32_e32 v141, v141
	v_add_f32_e32 v140, 1.0, v140
	v_add_f32_e32 v142, 1.0, v142
	v_add_f32_e32 v141, 1.0, v141
	v_rcp_f32_e32 v140, v140
	v_rcp_f32_e32 v169, v142
	v_rcp_f32_e32 v141, v141
	v_lshlrev_b32_e32 v142, 16, v143
	v_and_b32_e32 v143, 0xffff0000, v143
	v_pk_fma_f32 v[168:169], v[168:169], v[126:127], v[170:171]
	v_pk_fma_f32 v[170:171], v[140:141], v[122:123], v[142:143]
	v_cvt_pk_bf16_f32 v140, v162, v163
	v_cvt_pk_bf16_f32 v141, v168, v169
	v_cvt_pk_bf16_f32 v142, v164, v165
	v_cvt_pk_bf16_f32 v143, v170, v171
	global_store_dwordx4 v[160:161], v[140:143], off
	v_pk_mul_f32 v[160:161], v[164:165], v[164:165]
	s_nop 0
	v_pk_mul_f32 v[140:141], v[162:163], v[162:163]
	v_pk_mul_f32 v[142:143], v[168:169], v[168:169]
	v_add_f32_e32 v140, v140, v141
	v_add_f32_e32 v142, v142, v143
	v_pk_mul_f32 v[162:163], v[170:171], v[170:171]
	v_add_f32_e32 v140, v140, v142
	v_add_f32_e32 v141, v160, v161
	v_add_f32_e32 v162, v162, v163
	v_add_f32_e32 v140, v141, v140
	v_add_f32_e32 v140, v162, v140
	v_mov_b32_e32 v141, v140
	s_nop 1
	v_permlane16_swap_b32_e32 v141, v140
	s_waitcnt lgkmcnt(0)
	v_add_f32_e32 v140, v140, v141
	v_mov_b32_e32 v141, v140
	s_nop 1
	v_permlane32_swap_b32_e32 v141, v140
	s_and_saveexec_b64 s[72:73], s[6:7]
	s_cbranch_execz .LBB0_529
	s_waitcnt lgkmcnt(0)
	v_add_f32_e32 v142, v140, v141
	s_lshl_b32 s74, s19, 2
	v_lshlrev_b64 v[140:141], 8, v[146:147]
	s_ashr_i32 s75, s74, 31
	v_lshl_add_u64 v[140:141], s[26:27], 0, v[140:141]
	v_lshl_add_u64 v[140:141], s[74:75], 2, v[140:141]
	s_lshl_b32 s50, s37, 2
	v_lshl_add_u64 v[140:141], v[140:141], 0, s[50:51]
	global_store_dword v[140:141], v142, off
